# code placement: one 4-byte s_nop after the P0a fold so the P1/P3/P4 K-loop heads sit at 0 mod 8 bytes as in the baseline
# speedup vs baseline: 1.0158x; 1.0003x over previous
; __device__ __forceinline__ unsigned cvt_pk_bf16(float lo, float hi) { unsigned r; asm volatile("v_cvt_pk_bf16_f32 %0, %1, %2" : "=v"(r) : "v"(lo), "v"(hi)); return r; }
; #define LDS_FENCE() asm volatile("s_waitcnt lgkmcnt(0)" ::: "memory")
; __device__ __forceinline__ void transpose_item(const float* __restrict__ W, int ldw, int K, int N, const float* __restrict__ g, bf16_t* __restrict__ WT, float* scr, int item, int lane) {
;     const int nblk = N / 32, kb = item / nblk, nb = item - kb * nblk, k0 = 64 * kb, n0 = 32 * nb;
; #pragma unroll 8
;     for (int i = 0; i < 32; ++i) { const int kk = 2 * i + (lane >> 5); float v = W[(size_t)(k0 + kk) * ldw + n0 + (lane & 31)]; if (g) v *= g[k0 + kk]; scr[kk * 33 + (lane & 31)] = v; }
;     LDS_FENCE();
;     const int c = lane & 7;
; #pragma unroll
;     for (int j = 0; j < 4; ++j) { const int n = (lane >> 3) + 8 * j; const float* s = scr + (8 * c) * 33 + n;
;         u32x4 o; o.x = cvt_pk_bf16(s[0 * 33], s[1 * 33]); o.y = cvt_pk_bf16(s[2 * 33], s[3 * 33]); o.z = cvt_pk_bf16(s[4 * 33], s[5 * 33]); o.w = cvt_pk_bf16(s[6 * 33], s[7 * 33]);
;         *(u32x4*)(WT + (size_t)(n0 + n) * K + k0 + 8 * c) = o; }
; __global__ void __launch_bounds__(512, 2) fwd_kernel(Params p) {
;     ...
;         float* scr = (float*)lds + wave * (64 * 33);
;         int base = 0;
;         for (int j = 0; j < 2; ++j) transpose_job(w_in_moba + (size_t)j * D * NMOBA, NMOBA, D, NMOBA, g_mix + (2 * j + 1) * D, WT + wt_in(2 * j + 1), scr, base, gwave, gwaves, lane);
.Lfold_done:
	s_waitcnt vmcnt(0) lgkmcnt(0)
	s_nop 0
	v_lshlrev_b32_e32 v0, 3, v204
	s_mul_i32 s42, s33, 0x2100
	v_lshrrev_b32_e32 v179, 3, v148
	v_and_b32_e32 v10, 56, v0
	s_add_i32 s0, s42, 0
	v_mul_u32_u24_e32 v0, 0x84, v10
	v_lshlrev_b32_e32 v1, 2, v179
	s_abs_i32 s31, s30
	v_add3_u32 v180, s0, v0, v1
	v_cvt_f32_u32_e32 v0, s31
	v_and_b32_e32 v8, 31, v204
	v_lshl_add_u32 v6, v8, 2, s0
	s_sub_i32 s2, 0, s31
	v_rcp_iflag_f32_e32 v0, v0
	v_lshrrev_b32_e32 v4, 5, v148
	s_movk_i32 s43, 0x84
	v_mad_u32_u24 v181, v4, s43, v6
	v_mul_f32_e32 v0, 0x4f7ffffe, v0
	v_cvt_u32_f32_e32 v0, v0
	s_lshl_b32 s46, s68, 8
	s_mov_b32 s1, 0
	s_add_i32 s11, s10, s30
	v_readfirstlane_b32 s0, v0
	s_mul_i32 s2, s2, s0
	s_mul_hi_u32 s2, s0, s2
	v_or_b32_e32 v137, 2, v4
	v_or_b32_e32 v149, 4, v4
	v_or_b32_e32 v150, 6, v4
	v_or_b32_e32 v151, 8, v4
	v_or_b32_e32 v152, 10, v4
	v_or_b32_e32 v153, 12, v4
	v_or_b32_e32 v154, 14, v4
	v_or_b32_e32 v155, 16, v4
	v_or_b32_e32 v156, 18, v4
	v_or_b32_e32 v157, 20, v4
	v_or_b32_e32 v158, 22, v4
	v_or_b32_e32 v159, 24, v4
	v_or_b32_e32 v160, 26, v4
	v_or_b32_e32 v161, 28, v4
	v_or_b32_e32 v162, 30, v4
	v_or_b32_e32 v163, 32, v4
	v_or_b32_e32 v164, 34, v4
	v_or_b32_e32 v165, 36, v4
	v_or_b32_e32 v166, 38, v4
	v_or_b32_e32 v167, 40, v4
	v_or_b32_e32 v168, 42, v4
	v_or_b32_e32 v169, 44, v4
	v_or_b32_e32 v170, 46, v4
	v_or_b32_e32 v171, 48, v4
	v_or_b32_e32 v172, 50, v4
	v_or_b32_e32 v173, 52, v4
	v_or_b32_e32 v174, 54, v4
	v_or_b32_e32 v175, 56, v4
	v_or_b32_e32 v176, 58, v4
	v_or_b32_e32 v177, 60, v4
	v_or_b32_e32 v178, 62, v4
	v_add_u32_e32 v182, 0x108, v181
	v_add_u32_e32 v183, 0x210, v181
	v_add_u32_e32 v184, 0x318, v181
	v_add_u32_e32 v185, 0x420, v181
	v_add_u32_e32 v186, 0x528, v181
	v_add_u32_e32 v187, 0x630, v181
	v_add_u32_e32 v188, 0x738, v181
	v_add_u32_e32 v189, 0x840, v181
	v_add_u32_e32 v190, 0x948, v181
	v_add_u32_e32 v191, 0xa50, v181
	v_add_u32_e32 v192, 0xb58, v181
	v_add_u32_e32 v193, 0xc60, v181
	v_add_u32_e32 v194, 0xd68, v181
	v_add_u32_e32 v195, 0xe70, v181
	v_add_u32_e32 v196, 0xf78, v181
	v_add_u32_e32 v197, 0x1080, v181
	s_lshl_b32 s44, s68, 4
	s_add_i32 s45, s0, s2
	s_mov_b64 s[8:9], -1
	s_movk_i32 s47, 0x2800
	s_mov_b32 s4, 0
	s_mov_b32 s48, 0
	v_add_u32_e32 v198, 0x1188, v181
	v_add_u32_e32 v199, 0x1290, v181
	v_add_u32_e32 v200, 0x1398, v181
	v_add_u32_e32 v201, 0x14a0, v181
	v_add_u32_e32 v202, 0x15a8, v181
	v_add_u32_e32 v203, 0x16b0, v181
	v_add_u32_e32 v205, 0x17b8, v181
	v_add_u32_e32 v206, 0x18c0, v181
	v_add_u32_e32 v207, 0x19c8, v181
	v_add_u32_e32 v208, 0x1ad0, v181
	v_add_u32_e32 v209, 0x1bd8, v181
	v_add_u32_e32 v210, 0x1ce0, v181
	v_add_u32_e32 v211, 0x1de8, v181
	v_add_u32_e32 v212, 0x1ef0, v181
	v_add_u32_e32 v213, 0x1ff8, v181
	v_or_b32_e32 v214, 8, v179
	v_or_b32_e32 v215, 16, v179
	v_or_b32_e32 v216, 24, v179
	v_or_b32_e32 v217, s46, v179
	v_mov_b32_e32 v13, 0
	v_mov_b32_e32 v5, v4
	s_branch .LBB0_10
